# v15 plus a 7us start stagger of odd pm-pair CU groups also in P1 and P5 (de-synchronise epilogue store bursts)
# baseline (speedup 1.0000x reference)
;     __host__ __device__ bool next(int i, Unit& u) const {
;         const long L = (long)i * G + c; if (L >= nwg) return false;
;         int wgid = (int)L; { const int q = nwg / NXCD, r = nwg % NXCD, xcd = wgid % NXCD, off = wgid / NXCD; wgid = (xcd < r ? xcd * (q + 1) : r * (q + 1) + (xcd - r) * q) + off; }
;         const int nig = WGM * nN, gid = wgid / nig, fm = gid * WGM, gsz = (nM - fm) < WGM ? (nM - fm) : WGM;
;         u.pm = fm + ((wgid % nig) % gsz); u.pn = (wgid % nig) / gsz; if (rev) u.pm = nM - 1 - u.pm; return true;
; template <class Epi, class Sched, bool ALIGN_EPI = false, bool SP2 = false>
; __device__ __forceinline__ void gemm_phase(PG8_LAS unsigned char* lds, const Gemm g, const Sched& S, const Epi& E, const int wave_s) {
;     ...
;     if (!S.next(0, cur)) return;
.LBB0_193:
	v_writelane_b32 v255, s82, 5
	s_waitcnt lgkmcnt(0)
	s_barrier
	s_bfe_u32 s8, s10, 0x10004
	s_cmp_eq_u32 s8, 0
	s_cbranch_scc1 .Lstag_P1_done
	s_mul_i32 s8, s8, 2
.Lstag_P1_loop:
	s_sleep 127
	s_sub_u32 s8, s8, 1
	s_cmp_lg_u32 s8, 0
	s_cbranch_scc1 .Lstag_P1_loop
.Lstag_P1_done:
	v_mbcnt_lo_u32_b32 v0, -1, 0
	v_mbcnt_hi_u32_b32 v0, -1, v0
	s_cmpk_lt_i32 s10, 0x1980
	v_or_b32_e32 v8, s84, v0
	v_writelane_b32 v255, s83, 6
	s_cselect_b64 s[2:3], -1, 0
	s_cmpk_gt_i32 s10, 0x197f
	v_readfirstlane_b32 s8, v8
	s_cbranch_scc1 .LBB0_195
	s_ashr_i32 s4, s10, 31
	s_lshr_b32 s4, s4, 29
	s_add_i32 s4, s10, s4
	s_ashr_i32 s5, s4, 3
	s_and_b32 s4, s4, -8
	s_sub_i32 s4, s10, s4
	s_cmp_lt_i32 s4, 0
	s_movk_i32 s6, 0x331
	s_cselect_b32 s6, s6, 0x330
	s_mul_i32 s4, s4, s6
	s_add_i32 s4, s4, s5
	s_mul_hi_i32 s5, s4, 0x87878787
	s_lshr_b32 s6, s5, 31
	s_ashr_i32 s5, s5, 6
	s_add_i32 s5, s5, s6
	s_mul_hi_i32 s6, s4, 0x78787879
	s_lshr_b32 s7, s6, 31
	s_ashr_i32 s6, s6, 6
	s_add_i32 s6, s6, s7
	s_mulk_i32 s6, 0x88
	s_sub_i32 s4, s4, s6
	s_sext_i32_i16 s6, s4
	s_bfe_u32 s6, s6, 0x3001c
	s_add_i32 s6, s4, s6
	s_sext_i32_i16 s7, s6
	s_and_b32 s6, s6, 0xfff8
	s_sub_i32 s4, s6, s4
	s_lshl_b32 s5, s5, 3
	s_sext_i32_i16 s4, s4
	s_add_i32 s4, s5, s4
	s_ashr_i32 s70, s7, 3
	s_addk_i32 s4, 0x17f

; __device__ __forceinline__ int lane_now() { int l; asm volatile("v_mbcnt_lo_u32_b32 %0, -1, 0\n\tv_mbcnt_hi_u32_b32 %0, -1, %0" : "=v"(l)); return l; }
; #define PG8_WAIT_V(n) asm volatile("s_waitcnt vmcnt(" #n ")" ::: "memory")
; template <class Epi, class Sched, bool ALIGN_EPI = false, bool SP2 = false>
; __device__ __forceinline__ void gemm_phase(PG8_LAS unsigned char* lds, const Gemm g, const Sched& S, const Epi& E, const int wave_s) {
;     int tid_ = (wave_s << 6) | lane_now(); asm volatile("" : "+v"(tid_));
;     const int tid = tid_, wid = __builtin_amdgcn_readfirstlane(tid >> 6), lane = tid & 63, wr = wid >> 2, wc = wid & 3, fr = lane & 15, fq = lane >> 4;
;     const int K = g.K, nt = K / BK, lda = g.lda, ldb = g.ldb;
;     unsigned voffA[2], voffB[2];
; #pragma unroll
;     for (int i = 0; i < 2; ++i) { int R, C; stage_rc(tid * 16 + i * 8192, R, C); const int Rb = Epi::PERM ? ((R & ~31) + perm32(R & 31)) : R;
;         voffA[i] = (unsigned)(R * lda + C) * 2u; voffB[i] = (unsigned)(Rb * ldb + C) * 2u; }
;     const size_t kstep = (size_t)(BK * 2);
;     const size_t hA = (size_t)HALF * lda * 2, hB = (size_t)HALF * ldb * 2;
;     const size_t tA = 2 * hA, tB = 2 * hB;
;     const unsigned ldsw = (unsigned)wid * 1024u;
;     const int aoff = lds_byte(wr * 64 + fr, fq * 8), boff = lds_byte(wc * 32 + fr, fq * 8);
;     ...
;     Unit cur, nxt; int ui = 0; float pf[8] = {0.f, 0.f, 0.f, 0.f, 0.f, 0.f, 0.f, 0.f};
;     if (!S.next(0, cur)) return;
;     f32x4 acc[2][2][4][2];
; #pragma unroll
;     for (int a = 0; a < 2; ++a)
; #pragma unroll
;         for (int b = 0; b < 2; ++b)
; #pragma unroll
;             for (int m = 0; m < 4; ++m)
; #pragma unroll
;                 for (int n = 0; n < 2; ++n) acc[a][b][m][n] = (f32x4){0.f, 0.f, 0.f, 0.f};
;     bf16x8 At[4][2], B0[2][2], B1[2][2];
;     const char* cA = (const char*)g.A + (size_t)cur.pm * tA; const char* cB = (const char*)g.Bt + (size_t)cur.pn * tB;
;     S.a_ready(cur);
;     if constexpr (SP2) {
;         PG8_STAGE(PG8_SB(0, 0), cB, voffB); PG8_STAGE(PG8_SB(0, 1), cB + hB, voffB); PG8_STAGE(PG8_SA(0, 0), cA, voffA); PG8_STAGE(PG8_SA(0, 1), cA + hA, voffA);
;         if (wr == 1) PG8_BAR;
;         PG8_WAIT_V(2); PG8_BAR;
;         PG8_STAGE(PG8_SB(1, 0), cB + kstep, voffB); PG8_STAGE(PG8_SA(1, 0), cA + kstep, voffA); PG8_STAGE(PG8_SB(1, 1), cB + hB + kstep, voffB);
;         PG8_WAIT_V(6); PG8_BAR;
.LBB0_773:
	s_waitcnt lgkmcnt(0)
	s_barrier
	s_bfe_u32 s5, s10, 0x10004
	s_cmp_eq_u32 s5, 0
	s_cbranch_scc1 .Lstag_P5_done
	s_mul_i32 s5, s5, 2
.Lstag_P5_loop:
	s_sleep 127
	s_sub_u32 s5, s5, 1
	s_cmp_lg_u32 s5, 0
	s_cbranch_scc1 .Lstag_P5_loop
.Lstag_P5_done:
	v_mbcnt_lo_u32_b32 v0, -1, 0
	v_mbcnt_hi_u32_b32 v0, -1, v0
	s_cmpk_gt_i32 s10, 0x17ff
	v_or_b32_e32 v9, s84, v0
	s_nop 0
	v_readfirstlane_b32 s5, v9
	s_cbranch_scc1 .LBB0_791
	v_lshlrev_b32_e32 v0, 4, v9
	v_add_u32_e32 v1, 0x2000, v0
	v_ashrrev_i32_e32 v2, 31, v1
	v_lshrrev_b32_e32 v2, 22, v2
	v_add_u32_e32 v2, v1, v2
	v_ashrrev_i32_e32 v8, 10, v2
	v_mul_i32_i24_e32 v2, 0x400, v8
	v_sub_u32_e32 v1, v1, v2
	v_lshrrev_b32_e32 v2, 4, v1
	v_bitop3_b32 v1, v2, v1, 32 bitop3:0x6c
	v_ashrrev_i32_e32 v2, 31, v1
	v_lshrrev_b32_e32 v2, 26, v2
	v_add_u32_e32 v2, v1, v2
	v_lshlrev_b32_e32 v3, 3, v8
	v_ashrrev_i32_e32 v10, 6, v2
	v_and_b32_e32 v3, -16, v3
	v_add_u32_e32 v3, v10, v3
	v_and_b32_e32 v4, 3, v10
	s_mov_b32 s0, 0x1fffe0
	v_lshrrev_b32_e32 v5, 2, v3
	v_lshlrev_b32_e32 v6, 1, v3
	v_and_b32_e32 v2, 0xc0, v2
	v_and_or_b32 v4, v3, s0, v4
	v_and_b32_e32 v5, 4, v5
	v_and_b32_e32 v6, 24, v6
	v_sub_u32_e32 v1, v1, v2
	v_mov_b32_e32 v2, 1
	v_or3_b32 v4, v4, v5, v6
	v_lshlrev_b32_e32 v5, 5, v8
	v_ashrrev_i16_sdwa v1, v2, sext(v1) dst_sel:DWORD dst_unused:UNUSED_PAD src0_sel:DWORD src1_sel:BYTE_0
	v_and_b32_e32 v5, 32, v5
	v_bfe_i32 v11, v1, 0, 16
	v_add_lshl_u32 v1, v5, v11, 1
	v_lshl_add_u32 v128, v4, 11, v1
	v_lshl_add_u32 v130, v3, 11, v1
	v_bfe_i32 v1, v9, 27, 1
	v_lshrrev_b32_e32 v1, 22, v1
	v_add_u32_e32 v1, v0, v1
	v_and_b32_e32 v1, 0xfffffc00, v1
	v_sub_u32_e32 v0, v0, v1
	v_lshrrev_b32_e32 v1, 4, v0
	v_ashrrev_i32_e32 v3, 31, v9
	v_bitop3_b32 v0, v1, v0, 32 bitop3:0x6c
	v_lshrrev_b32_e32 v3, 26, v3
	v_ashrrev_i32_e32 v1, 31, v0
	v_add_u32_e32 v3, v9, v3
	v_lshrrev_b32_e32 v1, 26, v1
	v_ashrrev_i32_e32 v13, 6, v3
	v_add_u32_e32 v1, v0, v1
	v_lshlrev_b32_e32 v3, 3, v13
	v_ashrrev_i32_e32 v12, 6, v1
	v_and_b32_e32 v3, -16, v3
	v_add_u32_e32 v3, v12, v3
	v_and_b32_e32 v4, 3, v12
	s_ashr_i32 s12, s10, 31
	v_and_or_b32 v4, v3, s0, v4
	s_lshr_b32 s0, s12, 29
	s_add_i32 s0, s10, s0
	s_ashr_i32 s6, s5, 6
	s_ashr_i32 s1, s0, 3
	s_and_b32 s0, s0, -8
	s_ashr_i32 s9, s5, 8
	s_lshl_b32 s11, s6, 10
	s_sub_i32 s0, s10, s0
	s_cmp_lt_i32 s0, 0
	s_movk_i32 s13, 0x301
	s_cselect_b32 s4, s13, 0x300
	s_mul_i32 s0, s0, s4
	s_add_i32 s0, s0, s1
	s_ashr_i32 s1, s0, 31
	s_lshr_b32 s1, s1, 25
	s_add_i32 s1, s0, s1
	s_ashr_i32 s4, s1, 7
	s_and_b32 s1, s1, 0xffffff80
	s_sub_i32 s0, s0, s1
	s_bfe_i32 s1, s0, 0x80000
	s_bfe_u32 s1, s1, 0x3000c
	s_add_i32 s1, s0, s1
	s_lshl_b32 s7, s4, 3
	s_bfe_i32 s4, s1, 0x80000
	s_and_b32 s1, s1, 0xf8
	s_sub_i32 s0, s0, s1
	s_sext_i32_i16 s4, s4
	s_sext_i32_i8 s0, s0
	v_lshrrev_b32_e32 v5, 2, v3
	v_lshlrev_b32_e32 v6, 1, v3
	v_and_b32_e32 v1, 0xc0, v1
	s_lshr_b32 s4, s4, 3
	s_add_i32 s50, s7, s0
	v_and_b32_e32 v5, 4, v5
	v_and_b32_e32 v6, 24, v6
	v_sub_u32_e32 v0, v0, v1
	s_ashr_i32 s51, s50, 31
	s_bfe_i64 s[18:19], s[4:5], 0x100000
	v_or3_b32 v4, v4, v5, v6
	v_lshlrev_b32_e32 v5, 5, v13
	v_ashrrev_i16_sdwa v0, v2, sext(v0) dst_sel:DWORD dst_unused:UNUSED_PAD src0_sel:DWORD src1_sel:BYTE_0
	s_lshl_b64 s[0:1], s[50:51], 19
	s_lshl_b64 s[18:19], s[18:19], 19
	v_and_b32_e32 v5, 32, v5
	v_bfe_i32 v14, v0, 0, 16
	s_add_u32 s56, s54, s18
	v_add_lshl_u32 v0, v5, v14, 1
	s_addc_u32 s57, s55, s19
	s_add_i32 s34, s11, 0
	v_lshl_add_u32 v132, v4, 11, v0
	s_add_i32 m0, s34, 0x10000
	v_lshl_add_u32 v134, v3, 11, v0
	global_load_lds_dwordx4 v132, s[56:57]
	s_add_i32 m0, s34, 0x12000
	s_add_u32 s18, s56, 0x40000
	global_load_lds_dwordx4 v128, s[56:57]
	s_addc_u32 s19, s57, 0
	s_add_i32 m0, s34, 0x14000
	v_mov_b32_e32 v133, 0
	global_load_lds_dwordx4 v132, s[18:19]
	s_add_i32 m0, s34, 0x16000
	s_add_u32 s58, s14, s0
	s_addc_u32 s59, s15, s1
	s_add_i32 s35, s34, 0x2000
	global_load_lds_dwordx4 v128, s[18:19]
	s_mov_b32 m0, s34
	s_add_u32 s0, s58, 0x40000
	global_load_lds_dwordx4 v134, s[58:59]
	s_mov_b32 m0, s35
	s_addc_u32 s1, s59, 0
	s_add_i32 s60, s34, 0x4000
	global_load_lds_dwordx4 v130, s[58:59]
	s_mov_b32 m0, s60
	s_add_i32 s61, s34, 0x6000
	global_load_lds_dwordx4 v134, s[0:1]
	s_mov_b32 m0, s61
	v_mov_b32_e32 v129, v133
	global_load_lds_dwordx4 v130, s[0:1]
	v_mov_b32_e32 v135, v133
	v_mov_b32_e32 v131, v133
	s_cmp_eq_u32 s9, 1
	s_mov_b32 s62, 0
	v_lshl_add_u64 v[6:7], s[56:57], 0, v[132:133]
	v_lshl_add_u64 v[4:5], s[56:57], 0, v[128:129]
	v_lshl_add_u64 v[0:1], s[58:59], 0, v[134:135]
	s_cselect_b64 s[0:1], -1, 0
	s_cmp_lg_u32 s9, 1
	v_lshl_add_u64 v[2:3], s[58:59], 0, v[130:131]
	s_cbranch_scc1 .LBB0_776
	s_barrier
